# v23 + H2 segment-state combine loop software-pipelined (loads of next state issued before FMAs of current), bpermute temporaries moved to v240+
# baseline (speedup 1.0000x reference)
.LBB0_378:
	v_writelane_b32 v246, s52, 48
	s_cmp_lt_i32 s78, 4
	s_cselect_b64 s[2:3], -1, 0
	v_writelane_b32 v246, s53, 49
	s_add_u32 s72, s76, 0xc000000
	s_addc_u32 s73, s77, 0
	s_and_b64 s[2:3], s[2:3], s[0:1]
	v_writelane_b32 v246, s74, 50
	s_andn2_b64 vcc, exec, s[2:3]
	v_writelane_b32 v246, s88, 51
	s_nop 1
	v_writelane_b32 v246, s89, 52
	s_cbranch_vccnz .LBB0_397
	s_cmpk_gt_i32 s54, 0xff
	s_cbranch_scc1 .LBB0_397
	v_lshrrev_b32_e32 v6, 4, v170
	s_lshr_b32 s5, s48, 7
	v_and_b32_e32 v5, 15, v171
	v_lshlrev_b32_e32 v2, 2, v6
	s_lshl_b32 s8, s5, 4
	v_or_b32_e32 v9, s8, v2
	v_or_b32_e32 v150, s8, v5
	s_movk_i32 s8, 0x110
	s_bfe_u32 s6, s48, 0x10006
	v_mul_lo_u32 v10, v150, s8
	s_andn2_b32 s48, s48, 63
	s_add_i32 s8, 0, 0x1c400
	s_lshl_b32 s20, s55, 4
	s_lshl_b32 s0, s55, 5
	s_add_i32 s4, 0, 0x13c00
	v_and_b32_e32 v11, 48, v171
	s_add_i32 s9, s8, s48
	v_and_b32_e32 v16, 48, v170
	v_writelane_b32 v246, s2, 53
	v_lshrrev_b32_e32 v3, 2, v171
	s_add_i32 s0, s4, s0
	s_lshl_b32 s7, s6, 1
	s_lshl_b32 s21, s6, 6
	v_add_u32_e32 v14, s4, v11
	s_movk_i32 s4, 0x90
	s_add_i32 s12, 0, 0x11800
	v_add_u32_e32 v151, s9, v16
	v_or_b32_e32 v16, s20, v5
	v_lshl_or_b32 v24, s6, 5, v5
	v_writelane_b32 v246, s3, 54
	v_and_or_b32 v148, v3, 8, s20
	v_and_b32_e32 v4, 31, v171
	v_and_b32_e32 v7, 0xf8, v3
	v_lshlrev_b32_e32 v0, 4, v170
	v_mov_b32_e32 v1, 0
	v_or_b32_e32 v13, s21, v5
	v_mul_lo_u32 v15, v150, s4
	v_mul_lo_u32 v16, v16, s4
	v_or_b32_e32 v18, 48, v170
	v_or_b32_e32 v20, 0x70, v170
	v_or_b32_e32 v3, 7, v3
	s_cmp_le_u32 s7, s5
	v_or_b32_e32 v27, 1, v9
	v_or_b32_e32 v28, 2, v9
	v_or_b32_e32 v29, 3, v9
	v_or_b32_e32 v30, 16, v24
	v_mov_b32_e32 v33, 0x900
	v_writelane_b32 v246, s92, 55
	v_lshlrev_b32_e32 v149, 1, v4
	v_lshl_add_u64 v[78:79], s[38:39], 0, v[0:1]
	v_lshl_add_u32 v0, v6, 3, s0
	v_cmp_eq_u32_e64 s[0:1], 0, v4
	v_lshl_add_u32 v6, v148, 1, 0
	v_lshl_add_u32 v8, v4, 2, 0
	v_add_u32_e32 v10, 0, v10
	v_add_u32_e32 v12, 0, v11
	v_add_u32_e32 v15, s12, v15
	v_add_u32_e32 v16, 0, v16
	v_lshl_add_u32 v152, v148, 2, s8
	v_mul_u32_u24_e32 v17, 0x110, v5
	v_mul_u32_u24_e32 v19, 0x110, v18
	v_mul_u32_u24_e32 v21, 0x110, v20
	v_mul_u32_u24_e32 v4, 0x220, v4
	v_mul_lo_u32 v22, v148, s4
	v_mul_u32_u24_e32 v23, 0x90, v7
	v_mul_u32_u24_e32 v3, 0x90, v3
	s_cselect_b64 s[80:81], -1, 0
	v_mul_u32_u24_e32 v25, 0x110, v24
	v_mul_lo_u32 v26, v9, s4
	s_cmp_lt_u32 s7, s5
	v_mul_u32_u24_e32 v31, 0x110, v13
	v_mul_u32_u24_e32 v13, 0x90, v13
	v_mul_u32_u24_e32 v32, 0x90, v5
	v_mad_u32_u24 v5, v5, s4, v33
	v_mul_u32_u24_e32 v18, 0x90, v18
	v_mul_u32_u24_e32 v20, 0x90, v20
	v_or_b32_e32 v153, 0xc00, v7
	v_lshl_add_u32 v7, v24, 1, s12
	v_cmp_gt_u32_e64 s[4:5], v24, v9
	v_cmp_gt_u32_e64 s[6:7], v24, v27
	v_cmp_gt_u32_e64 s[8:9], v24, v28
	v_cmp_gt_u32_e64 s[10:11], v24, v29
	v_lshl_add_u32 v24, v30, 1, s12
	v_writelane_b32 v246, s93, 56
	s_mov_b32 s70, s86
	s_mov_b32 s58, s84
	s_mov_b32 s75, 0
	s_mov_b32 s59, s55
	v_cmp_gt_u32_e64 s[2:3], 32, v170
	s_cselect_b64 s[82:83], -1, 0
	v_cmp_gt_u32_e64 s[12:13], v30, v9
	v_cmp_gt_u32_e64 s[14:15], v30, v27
	v_cmp_gt_u32_e64 s[16:17], v30, v28
	v_cmp_gt_u32_e64 s[18:19], v30, v29
	v_or_b32_e32 v154, s20, v2
	v_xor_b32_e32 v155, 0xfbe, v149
	s_lshl_b32 s93, s21, 1
	v_lshlrev_b32_e32 v80, 1, v2
	s_mov_b32 s92, 0xffff0000
	s_mov_b32 s60, 0xbfb8aa3b
	v_add_u32_e32 v156, v6, v4
	v_add_u32_e32 v157, v8, v22
	v_add_u32_e32 v158, v8, v23
	v_add_u32_e32 v159, v8, v3
	v_add_u32_e32 v160, v7, v26
	v_add_u32_e32 v161, v24, v26
	v_add_u32_e32 v162, v14, v31
	v_add_u32_e32 v163, v15, v11
	v_add_u32_e32 v164, v12, v13
	v_add_u32_e32 v165, v16, v11
	v_add_u32_e32 v166, v12, v32
	v_add_u32_e32 v167, v12, v18
	v_add_u32_e32 v168, v12, v5
	v_add_u32_e32 v169, v12, v20
	v_add_u32_e32 v172, v0, v17
	v_add_u32_e32 v173, v0, v19
	v_add_u32_e32 v174, v0, v21
	v_mov_b32_e32 v175, 0xffe
	v_add_u32_e32 v176, v10, v11
	v_add_u32_e32 v177, v12, v25
	s_mov_b32 s61, s54
	s_mov_b32 s33, s54
	v_or_b32_e32 v240, 31, v170
	v_lshlrev_b32_e32 v240, 2, v240
	s_branch .LBB0_382

.LBB0_388:
	s_waitcnt vmcnt(0)
	v_lshlrev_b32_e32 v81, 16, v34
	v_and_b32_e32 v106, 0xffff0000, v34
	v_mul_f32_e64 v74, |v81|, s60
	v_lshlrev_b32_e32 v107, 16, v38
	v_and_b32_e32 v114, 0xffff0000, v38
	v_exp_f32_e32 v76, v74
	v_mul_f32_e64 v74, |v106|, s60
	v_mul_f32_e64 v104, |v107|, s60
	v_mul_f32_e64 v105, |v114|, s60
	v_exp_f32_e32 v77, v74
	v_exp_f32_e32 v104, v104
	v_exp_f32_e32 v105, v105
	v_add_f32_e32 v74, 1.0, v76
	v_add_f32_e32 v75, 1.0, v77
	v_add_f32_e32 v108, 1.0, v104
	v_add_f32_e32 v109, 1.0, v105
	v_rcp_f32_e32 v74, v74
	v_rcp_f32_e32 v75, v75
	v_rcp_f32_e32 v108, v108
	v_rcp_f32_e32 v109, v109
	v_cmp_le_f32_e32 vcc, 0, v106
	v_pk_mul_f32 v[110:111], v[76:77], v[74:75]
	v_cmp_le_f32_e64 s[22:23], 0, v81
	v_pk_mul_f32 v[112:113], v[104:105], v[108:109]
	v_cmp_le_f32_e64 s[24:25], 0, v114
	v_cmp_le_f32_e64 s[26:27], 0, v107
	v_cndmask_b32_e32 v77, v111, v75, vcc
	v_cndmask_b32_e64 v76, v110, v74, s[22:23]
	v_cndmask_b32_e64 v105, v113, v109, s[24:25]
	v_cndmask_b32_e64 v104, v112, v108, s[26:27]
	v_pk_fma_f32 v[76:77], v[94:95], v[76:77], v[82:83]
	v_pk_fma_f32 v[104:105], v[94:95], v[104:105], v[82:83]
	v_pk_mul_f32 v[104:105], v[76:77], v[104:105]
	v_lshlrev_b32_e32 v118, 16, v35
	s_nop 0
	v_mul_f32_dpp v104, v104, v104 row_shr:1 row_mask:0xf bank_mask:0xf
	v_mul_f32_dpp v105, v105, v105 row_shr:1 row_mask:0xf bank_mask:0xf
	v_and_b32_e32 v119, 0xffff0000, v35
	v_mul_f32_dpp v104, v104, v104 row_shr:2 row_mask:0xf bank_mask:0xf
	v_mul_f32_dpp v105, v105, v105 row_shr:2 row_mask:0xf bank_mask:0xf
	v_lshlrev_b32_e32 v126, 16, v39
	v_mul_f32_dpp v104, v104, v104 row_shr:4 row_mask:0xf bank_mask:0xf
	v_mul_f32_dpp v105, v105, v105 row_shr:4 row_mask:0xf bank_mask:0xf
	v_and_b32_e32 v127, 0xffff0000, v39
	v_mul_f32_dpp v104, v104, v104 row_shr:8 row_mask:0xf bank_mask:0xf
	v_mul_f32_dpp v105, v105, v105 row_shr:8 row_mask:0xf bank_mask:0xf
	v_mul_f32_e64 v116, |v126|, s60
	v_mul_f32_dpp v104, v104, v104 row_bcast:15 row_mask:0xa bank_mask:0xf
	v_mul_f32_dpp v105, v105, v105 row_bcast:15 row_mask:0xa bank_mask:0xf
	v_mul_f32_e64 v106, |v118|, s60
	v_mul_f32_e64 v107, |v119|, s60
	v_exp_f32_e32 v106, v106
	v_exp_f32_e32 v107, v107
	v_mul_f32_e64 v117, |v127|, s60
	v_exp_f32_e32 v116, v116
	v_exp_f32_e32 v117, v117
	v_add_f32_e32 v114, 1.0, v106
	v_add_f32_e32 v115, 1.0, v107
	v_rcp_f32_e32 v114, v114
	v_rcp_f32_e32 v115, v115
	v_add_f32_e32 v120, 1.0, v116
	v_add_f32_e32 v121, 1.0, v117
	v_rcp_f32_e32 v120, v120
	v_rcp_f32_e32 v121, v121
	v_pk_mul_f32 v[122:123], v[106:107], v[114:115]
	v_cmp_le_f32_e64 s[28:29], 0, v119
	v_cmp_le_f32_e64 s[30:31], 0, v118
	v_pk_mul_f32 v[124:125], v[116:117], v[120:121]
	v_cndmask_b32_e64 v107, v123, v115, s[28:29]
	v_cndmask_b32_e64 v106, v122, v114, s[30:31]
	v_cmp_le_f32_e64 s[34:35], 0, v127
	v_cmp_le_f32_e64 s[36:37], 0, v126
	v_pk_fma_f32 v[118:119], v[96:97], v[106:107], v[84:85]
	v_cndmask_b32_e64 v107, v125, v121, s[34:35]
	v_cndmask_b32_e64 v106, v124, v120, s[36:37]
	v_pk_fma_f32 v[106:107], v[96:97], v[106:107], v[84:85]
	v_pk_mul_f32 v[106:107], v[118:119], v[106:107]
	v_lshlrev_b32_e32 v130, 16, v36
	s_nop 0
	v_mul_f32_dpp v106, v106, v106 row_shr:1 row_mask:0xf bank_mask:0xf
	v_mul_f32_dpp v107, v107, v107 row_shr:1 row_mask:0xf bank_mask:0xf
	v_and_b32_e32 v131, 0xffff0000, v36
	v_mul_f32_dpp v106, v106, v106 row_shr:2 row_mask:0xf bank_mask:0xf
	v_mul_f32_dpp v107, v107, v107 row_shr:2 row_mask:0xf bank_mask:0xf
	v_lshlrev_b32_e32 v138, 16, v40
	v_mul_f32_dpp v106, v106, v106 row_shr:4 row_mask:0xf bank_mask:0xf
	v_mul_f32_dpp v107, v107, v107 row_shr:4 row_mask:0xf bank_mask:0xf
	v_and_b32_e32 v139, 0xffff0000, v40
	v_mul_f32_dpp v106, v106, v106 row_shr:8 row_mask:0xf bank_mask:0xf
	v_mul_f32_dpp v107, v107, v107 row_shr:8 row_mask:0xf bank_mask:0xf
	v_mul_f32_e64 v128, |v138|, s60
	v_mul_f32_dpp v106, v106, v106 row_bcast:15 row_mask:0xa bank_mask:0xf
	v_mul_f32_dpp v107, v107, v107 row_bcast:15 row_mask:0xa bank_mask:0xf
	v_mul_f32_e64 v116, |v130|, s60
	v_mul_f32_e64 v117, |v131|, s60
	v_exp_f32_e32 v116, v116
	v_exp_f32_e32 v117, v117
	v_mul_f32_e64 v129, |v139|, s60
	v_exp_f32_e32 v128, v128
	v_exp_f32_e32 v129, v129
	v_add_f32_e32 v126, 1.0, v116
	v_add_f32_e32 v127, 1.0, v117
	v_rcp_f32_e32 v126, v126
	v_rcp_f32_e32 v127, v127
	v_add_f32_e32 v132, 1.0, v128
	v_add_f32_e32 v133, 1.0, v129
	v_rcp_f32_e32 v132, v132
	v_rcp_f32_e32 v133, v133
	v_pk_mul_f32 v[134:135], v[116:117], v[126:127]
	v_cmp_le_f32_e64 s[38:39], 0, v131
	v_cmp_le_f32_e64 s[40:41], 0, v130
	v_pk_mul_f32 v[136:137], v[128:129], v[132:133]
	v_cndmask_b32_e64 v117, v135, v127, s[38:39]
	v_cndmask_b32_e64 v116, v134, v126, s[40:41]
	v_cmp_le_f32_e64 s[42:43], 0, v139
	v_cmp_le_f32_e64 s[44:45], 0, v138
	v_pk_fma_f32 v[128:129], v[98:99], v[116:117], v[86:87]
	v_cndmask_b32_e64 v117, v137, v133, s[42:43]
	v_cndmask_b32_e64 v116, v136, v132, s[44:45]
	v_pk_fma_f32 v[116:117], v[98:99], v[116:117], v[86:87]
	v_pk_mul_f32 v[116:117], v[128:129], v[116:117]
	v_lshlrev_b32_e32 v187, 16, v37
	s_nop 0
	v_mul_f32_dpp v116, v116, v116 row_shr:1 row_mask:0xf bank_mask:0xf
	v_mul_f32_dpp v117, v117, v117 row_shr:1 row_mask:0xf bank_mask:0xf
	v_and_b32_e32 v188, 0xffff0000, v37
	v_mul_f32_dpp v116, v116, v116 row_shr:2 row_mask:0xf bank_mask:0xf
	v_mul_f32_dpp v117, v117, v117 row_shr:2 row_mask:0xf bank_mask:0xf
	v_lshlrev_b32_e32 v189, 16, v41
	v_mul_f32_dpp v116, v116, v116 row_shr:4 row_mask:0xf bank_mask:0xf
	v_mul_f32_dpp v117, v117, v117 row_shr:4 row_mask:0xf bank_mask:0xf
	v_and_b32_e32 v190, 0xffff0000, v41
	v_mul_f32_dpp v116, v116, v116 row_shr:8 row_mask:0xf bank_mask:0xf
	v_mul_f32_dpp v117, v117, v117 row_shr:8 row_mask:0xf bank_mask:0xf
	v_mul_f32_e64 v140, |v189|, s60
	v_mul_f32_dpp v116, v116, v116 row_bcast:15 row_mask:0xa bank_mask:0xf
	v_mul_f32_dpp v117, v117, v117 row_bcast:15 row_mask:0xa bank_mask:0xf
	v_mul_f32_e64 v130, |v187|, s60
	v_mul_f32_e64 v131, |v188|, s60
	v_exp_f32_e32 v130, v130
	v_exp_f32_e32 v131, v131
	v_mul_f32_e64 v141, |v190|, s60
	v_exp_f32_e32 v140, v140
	v_exp_f32_e32 v141, v141
	v_add_f32_e32 v138, 1.0, v130
	v_add_f32_e32 v139, 1.0, v131
	v_rcp_f32_e32 v138, v138
	v_rcp_f32_e32 v139, v139
	v_add_f32_e32 v142, 1.0, v140
	v_add_f32_e32 v143, 1.0, v141
	v_rcp_f32_e32 v142, v142
	v_rcp_f32_e32 v143, v143
	v_pk_mul_f32 v[144:145], v[130:131], v[138:139]
	v_cmp_le_f32_e64 s[46:47], 0, v188
	v_cmp_le_f32_e64 s[48:49], 0, v187
	v_pk_mul_f32 v[146:147], v[140:141], v[142:143]
	v_cndmask_b32_e64 v131, v145, v139, s[46:47]
	v_cndmask_b32_e64 v130, v144, v138, s[48:49]
	v_cmp_le_f32_e64 s[50:51], 0, v190
	v_cmp_le_f32_e64 s[52:53], 0, v189
	v_pk_fma_f32 v[140:141], v[100:101], v[130:131], v[88:89]
	v_cndmask_b32_e64 v131, v147, v143, s[50:51]
	v_cndmask_b32_e64 v130, v146, v142, s[52:53]
	v_pk_fma_f32 v[130:131], v[100:101], v[130:131], v[88:89]
	v_pk_mul_f32 v[130:131], v[140:141], v[130:131]
	v_mov_b32_e32 v81, 1.0
	s_nop 0
	v_mul_f32_dpp v130, v130, v130 row_shr:1 row_mask:0xf bank_mask:0xf
	v_mul_f32_dpp v131, v131, v131 row_shr:1 row_mask:0xf bank_mask:0xf
	v_mov_b32_e32 v182, 1.0
	v_mul_f32_dpp v130, v130, v130 row_shr:2 row_mask:0xf bank_mask:0xf
	v_mul_f32_dpp v131, v131, v131 row_shr:2 row_mask:0xf bank_mask:0xf
	v_mov_b32_e32 v183, 1.0
	v_mul_f32_dpp v130, v130, v130 row_shr:4 row_mask:0xf bank_mask:0xf
	v_mul_f32_dpp v131, v131, v131 row_shr:4 row_mask:0xf bank_mask:0xf
	v_mov_b32_e32 v184, 1.0
	v_mul_f32_dpp v130, v130, v130 row_shr:8 row_mask:0xf bank_mask:0xf
	v_mul_f32_dpp v131, v131, v131 row_shr:8 row_mask:0xf bank_mask:0xf
	v_mov_b32_e32 v188, 1.0
	v_mov_b32_e32 v189, 1.0
	v_mov_b32_e32 v185, 1.0
	v_mov_b32_dpp v188, v130 row_bcast:15 row_mask:0xa bank_mask:0xf
	v_mov_b32_dpp v189, v131 row_bcast:15 row_mask:0xa bank_mask:0xf
	v_mov_b32_e32 v186, 1.0
	v_pk_mul_f32 v[130:131], v[130:131], v[188:189]
	v_mov_b32_e32 v187, 1.0
	v_mov_b32_e32 v188, 1.0
	v_mov_b32_dpp v81, v104 wave_shr:1 row_mask:0xf bank_mask:0xf
	ds_bpermute_b32 v241, v240, v104
	v_mov_b32_dpp v182, v105 wave_shr:1 row_mask:0xf bank_mask:0xf
	ds_bpermute_b32 v242, v240, v105
	v_mov_b32_dpp v183, v106 wave_shr:1 row_mask:0xf bank_mask:0xf
	ds_bpermute_b32 v243, v240, v106
	v_mov_b32_dpp v184, v107 wave_shr:1 row_mask:0xf bank_mask:0xf
	ds_bpermute_b32 v244, v240, v107
	v_mov_b32_dpp v185, v116 wave_shr:1 row_mask:0xf bank_mask:0xf
	ds_bpermute_b32 v245, v240, v116
	v_mov_b32_dpp v186, v117 wave_shr:1 row_mask:0xf bank_mask:0xf
	ds_bpermute_b32 v252, v240, v117
	v_mov_b32_dpp v187, v130 wave_shr:1 row_mask:0xf bank_mask:0xf
	ds_bpermute_b32 v253, v240, v130
	v_mov_b32_dpp v188, v131 wave_shr:1 row_mask:0xf bank_mask:0xf
	ds_bpermute_b32 v254, v240, v131
	s_cmpk_eq_i32 s55, 0x3c0
	s_cbranch_scc1 .LBB0_390
	v_add_u32_e32 v40, s55, v179
	v_add_u32_e32 v34, 64, v40
	v_add_u32_e32 v35, 1, v180
	v_add_u32_e32 v40, 0x41, v40
	v_cndmask_b32_e64 v34, v35, v34, s[20:21]
	v_cndmask_b32_e64 v40, v180, v40, s[20:21]
	v_ashrrev_i32_e32 v35, 31, v34
	v_ashrrev_i32_e32 v41, 31, v40
	v_lshlrev_b64 v[38:39], 13, v[34:35]
	v_lshlrev_b64 v[40:41], 13, v[40:41]
	v_lshl_add_u64 v[34:35], s[88:89], 0, v[38:39]
	v_lshl_add_u64 v[54:55], s[88:89], 0, v[40:41]
	v_lshl_add_u64 v[36:37], v[34:35], 0, v[0:1]
	v_lshl_add_u64 v[34:35], v[34:35], 0, v[92:93]
	v_lshl_add_u64 v[38:39], v[90:91], 0, v[38:39]
	v_lshl_add_u64 v[50:51], v[54:55], 0, v[0:1]
	global_load_dwordx4 v[42:45], v[36:37], off
	s_nop 0
	global_load_dwordx4 v[34:37], v[34:35], off offset:2048
	s_nop 0
	global_load_dwordx4 v[46:49], v[38:39], off
	s_nop 0
	global_load_dwordx4 v[50:53], v[50:51], off
	v_lshl_add_u64 v[38:39], v[54:55], 0, v[92:93]
	v_lshl_add_u64 v[54:55], v[90:91], 0, v[40:41]
	global_load_dwordx4 v[38:41], v[38:39], off offset:2048
	s_nop 0
	global_load_dwordx4 v[54:57], v[54:55], off
.LBB0_390:
	v_cndmask_b32_e32 v75, v75, v111, vcc
	v_cndmask_b32_e64 v74, v74, v110, s[22:23]
	v_pk_mul_f32 v[190:191], v[94:95], v[74:75]
	v_cndmask_b32_e64 v75, v109, v113, s[24:25]
	v_cndmask_b32_e64 v74, v108, v112, s[26:27]
	v_lshlrev_b32_e32 v112, 16, v66
	v_and_b32_e32 v113, 0xffff0000, v66
	v_lshlrev_b32_e32 v194, 16, v70
	v_and_b32_e32 v195, 0xffff0000, v70
	v_cndmask_b32_e64 v108, v81, 1.0, s[0:1]
	v_cndmask_b32_e64 v109, v182, 1.0, s[0:1]
	v_pk_mul_f32 v[192:193], v[94:95], v[74:75]
	s_waitcnt lgkmcnt(0)
	v_mov_b32_e32 v74, v241
	v_pk_mul_f32 v[196:197], v[76:77], v[108:109]
	v_cndmask_b32_e64 v77, v115, v123, s[28:29]
	v_cndmask_b32_e64 v76, v114, v122, s[30:31]
	v_mov_b32_e32 v70, v242
	v_pk_mul_f32 v[114:115], v[96:97], v[76:77]
	v_cndmask_b32_e64 v77, v121, v125, s[34:35]
	v_cndmask_b32_e64 v76, v120, v124, s[36:37]
	v_lshlrev_b32_e32 v120, 16, v67
	v_and_b32_e32 v121, 0xffff0000, v67
	v_cndmask_b32_e64 v66, v183, 1.0, s[0:1]
	v_cndmask_b32_e64 v67, v184, 1.0, s[0:1]
	v_pk_mul_f32 v[118:119], v[118:119], v[66:67]
	v_cndmask_b32_e64 v110, v185, 1.0, s[0:1]
	v_cndmask_b32_e64 v111, v186, 1.0, s[0:1]
	v_rcp_f32_e32 v184, v118
	v_rcp_f32_e32 v185, v119
	v_pk_mul_f32 v[128:129], v[128:129], v[110:111]
	v_cndmask_b32_e64 v111, v139, v145, s[46:47]
	v_cndmask_b32_e64 v110, v138, v144, s[48:49]
	v_pk_mul_f32 v[138:139], v[100:101], v[110:111]
	v_cndmask_b32_e64 v111, v143, v147, s[50:51]
	v_cndmask_b32_e64 v110, v142, v146, s[52:53]
	v_pk_mul_f32 v[142:143], v[100:101], v[110:111]
	v_cndmask_b32_e64 v110, v187, 1.0, s[0:1]
	v_cndmask_b32_e64 v111, v188, 1.0, s[0:1]
	v_pk_mul_f32 v[140:141], v[140:141], v[110:111]
	v_pk_mul_f32 v[184:185], v[114:115], v[184:185]
	v_rcp_f32_e32 v114, v128
	v_rcp_f32_e32 v115, v129
	v_pk_mul_f32 v[118:119], v[118:119], v[120:121]
	v_rcp_f32_e32 v120, v140
	v_rcp_f32_e32 v121, v141
	v_mov_b32_e32 v108, v244
	v_cndmask_b32_e64 v67, v127, v135, s[38:39]
	v_cndmask_b32_e64 v66, v126, v134, s[40:41]
	v_lshlrev_b32_e32 v134, 16, v68
	v_and_b32_e32 v135, 0xffff0000, v68
	v_rcp_f32_e32 v182, v196
	v_rcp_f32_e32 v183, v197
	v_pk_mul_f32 v[126:127], v[98:99], v[66:67]
	v_pk_mul_f32 v[128:129], v[128:129], v[134:135]
	v_lshlrev_b32_e32 v144, 16, v69
	v_and_b32_e32 v145, 0xffff0000, v69
	v_pk_mul_f32 v[126:127], v[126:127], v[114:115]
	v_cvt_pk_bf16_f32 v114, v128, v129
	v_rcp_f32_e32 v128, v104
	v_rcp_f32_e32 v129, v105
	v_pk_mul_f32 v[112:113], v[196:197], v[112:113]
	v_pk_mul_f32 v[134:135], v[140:141], v[144:145]
	v_pk_mul_f32 v[138:139], v[138:139], v[120:121]
	v_lshlrev_b32_e32 v124, 16, v71
	v_and_b32_e32 v125, 0xffff0000, v71
	v_pk_mul_f32 v[182:183], v[190:191], v[182:183]
	v_cvt_pk_bf16_f32 v112, v112, v113
	v_cvt_pk_bf16_f32 v113, v118, v119
	v_cvt_pk_bf16_f32 v115, v134, v135
	v_cvt_pk_bf16_f32 v120, v126, v127
	v_cvt_pk_bf16_f32 v121, v138, v139
	v_cvt_pk_bf16_f32 v118, v182, v183
	v_cvt_pk_bf16_f32 v119, v184, v185
	ds_write_b128 v156, v[112:115]
	ds_write_b128 v156, v[118:121] offset:17408
	v_rcp_f32_e32 v120, v106
	v_rcp_f32_e32 v121, v107
	v_pk_mul_f32 v[106:107], v[106:107], v[124:125]
	v_rcp_f32_e32 v124, v116
	v_rcp_f32_e32 v125, v117
	v_rcp_f32_e32 v134, v130
	v_rcp_f32_e32 v135, v131
	v_cndmask_b32_e64 v67, v133, v137, s[42:43]
	v_cndmask_b32_e64 v66, v132, v136, s[44:45]
	v_pk_mul_f32 v[112:113], v[192:193], v[128:129]
	v_pk_mul_f32 v[132:133], v[98:99], v[66:67]
	v_mov_b32_e32 v114, v182
	v_mov_b32_e32 v115, v112
	v_pk_mul_f32 v[122:123], v[96:97], v[76:77]
	v_mov_b32_e32 v66, v245
	v_pk_mul_f32 v[118:119], v[114:115], v[74:75] op_sel_hi:[1,0]
	v_mov_b32_e32 v114, v183
	v_mov_b32_e32 v115, v113
	v_lshlrev_b32_e32 v136, 16, v72
	v_and_b32_e32 v137, 0xffff0000, v72
	v_mov_b32_e32 v72, v252
	v_lshlrev_b32_e32 v146, 16, v73
	v_and_b32_e32 v147, 0xffff0000, v73
	v_pk_mul_f32 v[128:129], v[114:115], v[70:71] op_sel_hi:[1,0]
	v_pk_mul_f32 v[114:115], v[122:123], v[120:121]
	v_pk_mul_f32 v[124:125], v[132:133], v[124:125]
	v_pk_mul_f32 v[134:135], v[142:143], v[134:135]
	v_mov_b32_e32 v76, v243
	v_mov_b32_e32 v68, v253
	v_pk_mul_f32 v[104:105], v[104:105], v[194:195]
	v_mov_b32_e32 v120, v184
	v_mov_b32_e32 v121, v114
	v_mov_b32_e32 v122, v185
	v_mov_b32_e32 v123, v115
	v_pk_mul_f32 v[116:117], v[116:117], v[136:137]
	v_mov_b32_e32 v132, v126
	v_mov_b32_e32 v133, v124
	v_pk_mul_f32 v[130:131], v[130:131], v[146:147]
	v_mov_b32_e32 v136, v138
	v_mov_b32_e32 v137, v134
	v_mov_b32_e32 v110, v254
	v_pk_mul_f32 v[120:121], v[120:121], v[76:77] op_sel_hi:[1,0]
	v_pk_mul_f32 v[122:123], v[122:123], v[108:109] op_sel_hi:[1,0]
	v_pk_mul_f32 v[132:133], v[132:133], v[66:67] op_sel_hi:[1,0]
	v_mov_b32_e32 v126, v127
	v_mov_b32_e32 v127, v125
	v_pk_mul_f32 v[136:137], v[136:137], v[68:69] op_sel_hi:[1,0]
	v_cvt_pk_bf16_f32 v104, v104, v105
	v_cvt_pk_bf16_f32 v105, v106, v107
	v_cvt_pk_bf16_f32 v106, v116, v117
	v_cvt_pk_bf16_f32 v107, v130, v131
	v_cvt_pk_bf16_f32 v67, v118, v119
	v_cvt_pk_bf16_f32 v69, v128, v129
	v_add_u32_e32 v71, 0x8800, v157
	v_pk_mul_f32 v[126:127], v[126:127], v[72:73] op_sel_hi:[1,0]
	v_mov_b32_e32 v138, v139
	v_mov_b32_e32 v139, v135
	v_cvt_pk_bf16_f32 v112, v112, v113
	v_cvt_pk_bf16_f32 v113, v114, v115
	v_cvt_pk_bf16_f32 v114, v124, v125
	v_cvt_pk_bf16_f32 v115, v134, v135
	ds_write_b128 v156, v[104:107] offset:272
	ds_write_b128 v156, v[112:115] offset:17680
	ds_write2_b32 v71, v67, v69 offset1:36
	v_cvt_pk_bf16_f32 v67, v120, v121
	v_cvt_pk_bf16_f32 v69, v122, v123
	v_pk_mul_f32 v[138:139], v[138:139], v[110:111] op_sel_hi:[1,0]
	ds_write2_b32 v71, v67, v69 offset0:72 offset1:108
	v_cvt_pk_bf16_f32 v67, v132, v133
	v_cvt_pk_bf16_f32 v69, v126, v127
	ds_write2_b32 v71, v67, v69 offset0:144 offset1:180
	v_cvt_pk_bf16_f32 v67, v136, v137
	v_cvt_pk_bf16_f32 v69, v138, v139
	ds_write2_b32 v71, v67, v69 offset0:216 offset1:252
	s_and_saveexec_b64 s[22:23], s[0:1]
	s_cbranch_execz .LBB0_392
	v_mov_b32_e32 v75, v70
	v_mov_b32_e32 v77, v108
	v_mov_b32_e32 v67, v72
	v_mov_b32_e32 v69, v110
	ds_write_b128 v152, v[74:77]
	ds_write_b128 v152, v[66:69] offset:16
